# v31 + branch-GEMM first two counted waits per z-unit relaxed to vmcnt(16) so the gate loads stay in flight (prologue drained once)
# speedup vs baseline: 1.0055x; 1.0035x over previous
; __device__ __forceinline__ int lane_id_v() { int l; asm volatile("v_mbcnt_lo_u32_b32 %0, -1, 0\n\tv_mbcnt_hi_u32_b32 %0, -1, %0" : "=v"(l)); return l; }
; #define PG8_STAGE(bufoff, gbase, voff) do { _Pragma("unroll") for (int _i = 0; _i < 2; ++_i) \
;         __builtin_amdgcn_global_load_lds((const unsigned*)((const char*)(gbase) + (voff)[_i]), (LAS unsigned*)(lds + (bufoff) + ldsw + _i * 8192), 16, 0, 0); } while (0)
; #define PG8_WAIT_V(n) asm volatile("s_waitcnt vmcnt(" #n ")" ::: "memory")
; #define PG8_BAR __builtin_amdgcn_s_barrier()
; template <class Epi, class Sched, bool HALFN = false>
; __device__ __forceinline__ void gemm_phase(LAS unsigned char* lds, const Gemm g, const Sched& S, const Epi& E, int wave_s) {
;     ...
;     if constexpr (HALFN) {
; #pragma unroll
;         for (int a = 0; a < 2; ++a)
; #pragma unroll
;             for (int m = 0; m < 4; ++m)
; #pragma unroll
;                 for (int n = 0; n < 2; ++n) yacc[a][m][n] = (f32x4){0.f, 0.f, 0.f, 0.f};
;     }
;     ...
;     PG8_STAGE(PG8_SB(1, 0), cB + kstep, voffB); PG8_STAGE(PG8_SA(1, 0), cA + kstep, voffA); PG8_STAGE(PG8_SB(1, 1), cB + bh1 + kstep, voffB);
;     PG8_WAIT_V(6); PG8_BAR;
;     const int l3 = lane_id_v();
;     const int aoff = lds_byte(wr * 64 + (l3 & 15), (l3 >> 4) * 8), boff = lds_byte(wc * 32 + (l3 & 15), (l3 >> 4) * 8);
.LBB0_883:
	s_add_u32 s16, s4, 0x372fe800
	s_addc_u32 s17, s5, 0
	s_add_i32 m0, s31, 0x18000
	v_lshl_add_u64 v[42:43], v[42:43], 0, s[50:51]
	s_waitcnt vmcnt(2)
	s_barrier
	global_load_lds_dwordx4 v[42:43], off
	v_lshl_add_u64 v[40:41], v[40:41], 0, s[50:51]
	s_add_i32 m0, s31, 0x1a000
	s_add_i32 s59, s31, 0x8000
	global_load_lds_dwordx4 v[40:41], off
	v_lshl_add_u64 v[36:37], v[36:37], 0, s[50:51]
	s_mov_b32 m0, s59
	s_add_i32 s62, s31, 0xa000
	global_load_lds_dwordx4 v[36:37], off
	v_lshl_add_u64 v[36:37], v[38:39], 0, s[50:51]
	s_mov_b32 m0, s62
	s_add_i32 s64, s31, 0x1c000
	global_load_lds_dwordx4 v[36:37], off
	s_mov_b32 m0, s64
	s_add_i32 s65, s31, 0x1e000
	global_load_lds_dwordx4 v[42:43], off
	s_mov_b32 m0, s65
	s_lshl_b32 s4, s6, 13
	global_load_lds_dwordx4 v[40:41], off
	s_waitcnt vmcnt(6)
	s_barrier
	v_mbcnt_lo_u32_b32 v1, -1, 0
	v_mbcnt_hi_u32_b32 v1, -1, v1
	v_mov_b32_e32 v106, 0
	v_and_b32_e32 v36, 15, v1
	v_or_b32_e32 v37, s45, v36
	v_ashrrev_i32_e32 v38, 6, v1
	v_lshlrev_b32_e32 v39, 6, v37
	v_and_b32_e32 v40, 48, v1
	v_lshlrev_b32_e32 v37, 2, v37
	v_and_or_b32 v39, v39, s63, v40
	v_lshl_add_u32 v41, v38, 10, s4
	v_and_b32_e32 v37, 32, v37
	s_lshr_b32 s4, s46, 3
	v_lshlrev_b32_e32 v1, 2, v1
	v_bitop3_b32 v37, v39, v41, v37 bitop3:0xde
	v_lshl_or_b32 v36, v36, 6, v40
	v_add_lshl_u32 v38, v38, s4, 10
	v_and_b32_e32 v1, 32, v1
	s_cmp_lt_u32 s9, 4
	v_bitop3_b32 v1, v36, v38, v1 bitop3:0xde
	v_add_u32_e32 v176, 0, v37
	s_cselect_b64 s[18:19], -1, 0
	s_ashr_i32 s67, s0, 31
	s_mov_b32 s9, s49
	s_mov_b32 s13, 0
	s_mov_b32 s68, 1
	s_movk_i32 s69, 0x400
	s_mov_b32 s70, 0
	v_mov_b32_e32 v107, v106
	v_mov_b32_e32 v110, v106
	v_mov_b32_e32 v111, v106
	v_mov_b32_e32 v108, v106
	v_mov_b32_e32 v109, v106
	v_mov_b32_e32 v112, v106
	v_mov_b32_e32 v113, v106
	v_mov_b32_e32 v114, v106
	v_mov_b32_e32 v115, v106
	v_mov_b32_e32 v118, v106
	v_mov_b32_e32 v119, v106
	v_mov_b32_e32 v116, v106
	v_mov_b32_e32 v117, v106
	v_mov_b32_e32 v120, v106
	v_mov_b32_e32 v121, v106
	v_mov_b32_e32 v122, v106
	v_mov_b32_e32 v123, v106
	v_mov_b32_e32 v126, v106
	v_mov_b32_e32 v127, v106
	v_mov_b32_e32 v124, v106
	v_mov_b32_e32 v125, v106
	v_mov_b32_e32 v128, v106
	v_mov_b32_e32 v129, v106
	v_mov_b32_e32 v130, v106
	v_mov_b32_e32 v131, v106
	v_mov_b32_e32 v134, v106
	v_mov_b32_e32 v135, v106
	v_mov_b32_e32 v132, v106
	v_mov_b32_e32 v133, v106
	v_mov_b32_e32 v136, v106
	v_mov_b32_e32 v137, v106
	v_mov_b32_e32 v138, v106
	v_mov_b32_e32 v139, v106
	v_mov_b32_e32 v142, v106
	v_mov_b32_e32 v143, v106
	v_mov_b32_e32 v140, v106
	v_mov_b32_e32 v141, v106
	v_mov_b32_e32 v144, v106
	v_mov_b32_e32 v145, v106
	v_mov_b32_e32 v146, v106
	v_mov_b32_e32 v147, v106
	v_mov_b32_e32 v150, v106
	v_mov_b32_e32 v151, v106
	v_mov_b32_e32 v148, v106
	v_mov_b32_e32 v149, v106
	v_mov_b32_e32 v152, v106
	v_mov_b32_e32 v153, v106
	v_mov_b32_e32 v154, v106
	v_mov_b32_e32 v155, v106
	v_mov_b32_e32 v158, v106
	v_mov_b32_e32 v159, v106
	v_mov_b32_e32 v156, v106
	v_mov_b32_e32 v157, v106
	v_mov_b32_e32 v160, v106
	v_mov_b32_e32 v161, v106
	v_mov_b32_e32 v162, v106
	v_mov_b32_e32 v163, v106
	v_mov_b32_e32 v164, v106
	v_mov_b32_e32 v165, v106
	v_mov_b32_e32 v166, v106
	v_mov_b32_e32 v167, v106
	v_mov_b32_e32 v168, v106
	v_mov_b32_e32 v169, v106
	s_waitcnt vmcnt(0)
	s_branch .LBB0_886

; #define PG8_STAGE(bufoff, gbase, voff) do { _Pragma("unroll") for (int _i = 0; _i < 2; ++_i) \
;         __builtin_amdgcn_global_load_lds((const unsigned*)((const char*)(gbase) + (voff)[_i]), (LAS unsigned*)(lds + (bufoff) + ldsw + _i * 8192), 16, 0, 0); } while (0)
; #define PG8_LDA(dst, b, h) do { _Pragma("unroll") for (int m = 0; m < 4; ++m) _Pragma("unroll") for (int k = 0; k < 2; ++k) dst[m][k] = *(const LAS bf16x8*)(lds + PG8_SA(b, h) + aoff + m * 2048 + k * 1024); } while (0)
; #define PG8_LDB(dst, b, h) do { _Pragma("unroll") for (int n = 0; n < 2; ++n) _Pragma("unroll") for (int k = 0; k < 2; ++k) dst[n][k] = *(const LAS bf16x8*)(lds + PG8_SB(b, h) + boff + n * 2048 + k * 1024); } while (0)
; #define PG8_MMA(ai, bj, At, Bt) do { __builtin_amdgcn_s_setprio(1); _Pragma("unroll") for (int m = 0; m < 4; ++m) _Pragma("unroll") for (int n = 0; n < 2; ++n) _Pragma("unroll") for (int k = 0; k < 2; ++k) \
;         acc[ai][bj][m][n] = __builtin_amdgcn_mfma_f32_16x16x32_bf16(Bt[n][k], At[m][k], acc[ai][bj][m][n], 0, 0, 0); __builtin_amdgcn_s_setprio(0); } while (0)
; #define PG8_WAIT_V(n) asm volatile("s_waitcnt vmcnt(" #n ")" ::: "memory")
; #define PG8_WAIT_L(n) asm volatile("s_waitcnt lgkmcnt(" #n ")" ::: "memory")
; #define PG8_BAR __builtin_amdgcn_s_barrier()
; template <class Epi, class Sched, bool HALFN = false>
; __device__ __forceinline__ void gemm_phase(LAS unsigned char* lds, const Gemm g, const Sched& S, const Epi& E, int wave_s) {
;     ...
;         for (int t = 0; t < nt; t += 2) {
;             const bool last = (t == nt - 2);
;             const char* a1 = cA + (size_t)(t + 1) * kstep;
;             const char* a2 = last ? nA : cA + (size_t)(t + 2) * kstep; const char* b2 = last ? nB : cB + (size_t)(t + 2) * kstep;
;             const char* a3 = a2 + kstep; const char* b3 = b2 + kstep;
;             PG8_LDB(B0, 0, 0); if (!HALFN) PG8_LDB(B1, 0, 1); PG8_SCHED; PG8_LDA(At, 0, 0); PG8_STAGE(PG8_SA(1, 1), a1 + hstep, voffA);
;             PG8_WAIT_V(8); PG8_WAIT_L(0); PG8_BAR; PG8_MMA(0, 0, At, B0); if (!HALFN) PG8_MMA(0, 1, At, B1); PG8_BAR; PG8_SCHED;
;             PG8_LDA(At, 0, 1); PG8_STAGE(PG8_SB(0, 0), b2, voffB); PG8_STAGE(PG8_SB(0, 1), b2 + bh1, voffB); PG8_STAGE(PG8_SA(0, 0), a2, voffA);
;             PG8_WAIT_V(8); PG8_WAIT_L(0); PG8_BAR; PG8_MMA(1, 0, At, B0); if (!HALFN) PG8_MMA(1, 1, At, B1); PG8_BAR; PG8_SCHED;
.LBB0_890:
	s_lshl_b64 s[26:27], s[48:49], 20
	s_add_u32 s23, s38, s26
	s_addc_u32 s29, s39, s27
	s_ashr_i32 s21, s20, 31
	s_lshl_b64 s[26:27], s[20:21], 17
	s_add_u32 s26, s23, s26
	s_addc_u32 s27, s29, s27
	s_and_b64 s[4:5], s[4:5], exec
	s_cselect_b32 s5, s27, s37
	s_cselect_b32 s4, s26, s36
	s_add_i32 s48, 0, 0x10000
	v_add_u32_e32 v44, s48, v1
	ds_read_b128 v[46:49], v44
	ds_read_b128 v[50:53], v44 offset:1024
	ds_read_b128 v[54:57], v44 offset:2048
	ds_read_b128 v[58:61], v44 offset:3072
	s_add_u32 s74, s34, 0x20080
	s_addc_u32 s75, s35, 0
	s_add_i32 s52, s31, 0xc000
	v_lshl_add_u64 v[86:87], s[74:75], 0, v[100:101]
	s_mov_b32 m0, s52
	s_add_i32 s21, s31, 0xe000
	ds_read_b128 v[36:39], v176
	ds_read_b128 v[40:43], v176 offset:1024
	ds_read_b128 v[62:65], v176 offset:2048
	ds_read_b128 v[66:69], v176 offset:3072
	ds_read_b128 v[70:73], v176 offset:4096
	ds_read_b128 v[74:77], v176 offset:5120
	ds_read_b128 v[78:81], v176 offset:6144
	ds_read_b128 v[82:85], v176 offset:7168
	global_load_lds_dwordx4 v[86:87], off
	v_lshl_add_u64 v[86:87], s[74:75], 0, v[102:103]
	s_mov_b32 m0, s21
	s_nop 0
	global_load_lds_dwordx4 v[86:87], off
	s_waitcnt vmcnt(16)
	s_waitcnt lgkmcnt(0)
	s_barrier
	s_setprio 1
	s_waitcnt lgkmcnt(0)
	v_mfma_f32_16x16x32_bf16 v[86:89], v[46:49], v[36:39], 0
	v_mfma_f32_16x16x32_bf16 v[36:39], v[54:57], v[36:39], 0
	v_mfma_f32_16x16x32_bf16 v[90:93], v[58:61], v[40:43], v[36:39]
	v_mfma_f32_16x16x32_bf16 v[36:39], v[46:49], v[62:65], 0
	v_mfma_f32_16x16x32_bf16 v[94:97], v[50:53], v[66:69], v[36:39]
	v_mfma_f32_16x16x32_bf16 v[36:39], v[54:57], v[62:65], 0
	v_mfma_f32_16x16x32_bf16 v[62:65], v[58:61], v[66:69], v[36:39]
	v_mfma_f32_16x16x32_bf16 v[36:39], v[46:49], v[70:73], 0
	v_mfma_f32_16x16x32_bf16 v[66:69], v[50:53], v[74:77], v[36:39]
	v_mfma_f32_16x16x32_bf16 v[36:39], v[54:57], v[70:73], 0
	v_mfma_f32_16x16x32_bf16 v[70:73], v[58:61], v[74:77], v[36:39]
	v_mfma_f32_16x16x32_bf16 v[36:39], v[46:49], v[78:81], 0
	v_mfma_f32_16x16x32_bf16 v[74:77], v[50:53], v[82:85], v[36:39]
	v_mfma_f32_16x16x32_bf16 v[36:39], v[54:57], v[78:81], 0
	v_mfma_f32_16x16x32_bf16 v[86:89], v[50:53], v[40:43], v[86:89]
	v_mfma_f32_16x16x32_bf16 v[78:81], v[58:61], v[82:85], v[36:39]
	s_setprio 0
	s_barrier
	s_nop 3
	v_lshl_add_u64 v[36:37], s[36:37], 0, v[18:19]
	s_mov_b64 s[74:75], 0x100
	s_add_i32 s48, s48, s41
	v_lshl_add_u64 v[40:41], v[36:37], 0, s[74:75]
	s_mov_b32 m0, s48
	v_lshl_add_u64 v[38:39], s[36:37], 0, v[104:105]
	s_add_i32 s23, s48, 0x2000
	ds_read_b128 v[82:85], v176 offset:16384
	ds_read_b128 v[170:173], v176 offset:17408
	ds_read_b128 v[178:181], v176 offset:18432
	ds_read_b128 v[182:185], v176 offset:19456
	ds_read_b128 v[186:189], v176 offset:20480
	ds_read_b128 v[190:193], v176 offset:21504
	ds_read_b128 v[194:197], v176 offset:22528
	ds_read_b128 v[208:211], v176 offset:23552
	global_load_lds_dwordx4 v[40:41], off
	v_lshl_add_u64 v[42:43], v[38:39], 0, s[74:75]
	s_mov_b32 m0, s23
	s_nop 0
	global_load_lds_dwordx4 v[42:43], off
	s_mov_b32 m0, s47
	s_nop 0
	global_load_lds_dwordx4 v[40:41], off
	s_mov_b32 m0, s55
	v_lshl_add_u64 v[40:41], s[34:35], 0, v[100:101]
	global_load_lds_dwordx4 v[42:43], off
	v_lshl_add_u64 v[42:43], v[40:41], 0, s[74:75]
	s_mov_b32 m0, s31
	s_nop 0
	global_load_lds_dwordx4 v[42:43], off
	v_lshl_add_u64 v[42:43], s[34:35], 0, v[102:103]
	v_lshl_add_u64 v[98:99], v[42:43], 0, s[74:75]
	s_mov_b32 m0, s56
	s_nop 0
	global_load_lds_dwordx4 v[98:99], off
	s_waitcnt vmcnt(16)
	s_waitcnt lgkmcnt(0)
	s_barrier
	s_setprio 1
	s_waitcnt lgkmcnt(0)
	v_mfma_f32_16x16x32_bf16 v[212:215], v[46:49], v[82:85], 0
	v_mfma_f32_16x16x32_bf16 v[82:85], v[54:57], v[82:85], 0
	v_mfma_f32_16x16x32_bf16 v[212:215], v[50:53], v[170:173], v[212:215]
	v_mfma_f32_16x16x32_bf16 v[82:85], v[58:61], v[170:173], v[82:85]
	v_mfma_f32_16x16x32_bf16 v[170:173], v[46:49], v[178:181], 0
	v_mfma_f32_16x16x32_bf16 v[178:181], v[54:57], v[178:181], 0
	v_mfma_f32_16x16x32_bf16 v[170:173], v[50:53], v[182:185], v[170:173]
	v_mfma_f32_16x16x32_bf16 v[178:181], v[58:61], v[182:185], v[178:181]
	v_mfma_f32_16x16x32_bf16 v[182:185], v[46:49], v[186:189], 0
	v_mfma_f32_16x16x32_bf16 v[46:49], v[46:49], v[194:197], 0
	v_mfma_f32_16x16x32_bf16 v[182:185], v[50:53], v[190:193], v[182:185]
	v_mfma_f32_16x16x32_bf16 v[46:49], v[50:53], v[208:211], v[46:49]
	v_mfma_f32_16x16x32_bf16 v[50:53], v[54:57], v[194:197], 0
	v_mfma_f32_16x16x32_bf16 v[186:189], v[54:57], v[186:189], 0
	v_mfma_f32_16x16x32_bf16 v[50:53], v[58:61], v[208:211], v[50:53]
	v_mfma_f32_16x16x32_bf16 v[186:189], v[58:61], v[190:193], v[186:189]
	s_setprio 0
	s_barrier
	s_add_i32 s29, 0, 0x18000
	v_add_u32_e32 v45, s29, v1
	ds_read_b128 v[54:57], v45
	ds_read_b128 v[58:61], v45 offset:1024
	ds_read_b128 v[190:193], v45 offset:2048
	ds_read_b128 v[194:197], v45 offset:3072
	s_add_u32 s36, s34, 0x20100
	s_addc_u32 s37, s35, 0
	s_mov_b32 m0, s57
	v_lshl_add_u64 v[98:99], s[36:37], 0, v[100:101]
	ds_read_b128 v[208:211], v176 offset:32768
	ds_read_b128 v[216:219], v176 offset:33792
	ds_read_b128 v[220:223], v176 offset:34816
	ds_read_b128 v[224:227], v176 offset:35840
	ds_read_b128 v[228:231], v176 offset:36864
	ds_read_b128 v[232:235], v176 offset:37888
	ds_read_b128 v[236:239], v176 offset:38912
	ds_read_b128 v[240:243], v176 offset:39936
	global_load_lds_dwordx4 v[98:99], off
	v_lshl_add_u64 v[98:99], s[36:37], 0, v[102:103]
	s_mov_b32 m0, s58
	s_nop 0
	global_load_lds_dwordx4 v[98:99], off
	s_waitcnt vmcnt(8)
	s_waitcnt lgkmcnt(0)
	s_barrier
; #define PG8_STAGE(bufoff, gbase, voff) do { _Pragma("unroll") for (int _i = 0; _i < 2; ++_i) \
;         __builtin_amdgcn_global_load_lds((const unsigned*)((const char*)(gbase) + (voff)[_i]), (LAS unsigned*)(lds + (bufoff) + ldsw + _i * 8192), 16, 0, 0); } while (0)
; #define PG8_LDA(dst, b, h) do { _Pragma("unroll") for (int m = 0; m < 4; ++m) _Pragma("unroll") for (int k = 0; k < 2; ++k) dst[m][k] = *(const LAS bf16x8*)(lds + PG8_SA(b, h) + aoff + m * 2048 + k * 1024); } while (0)
; #define PG8_LDB(dst, b, h) do { _Pragma("unroll") for (int n = 0; n < 2; ++n) _Pragma("unroll") for (int k = 0; k < 2; ++k) dst[n][k] = *(const LAS bf16x8*)(lds + PG8_SB(b, h) + boff + n * 2048 + k * 1024); } while (0)
; #define PG8_MMA(ai, bj, At, Bt) do { __builtin_amdgcn_s_setprio(1); _Pragma("unroll") for (int m = 0; m < 4; ++m) _Pragma("unroll") for (int n = 0; n < 2; ++n) _Pragma("unroll") for (int k = 0; k < 2; ++k) \
;         acc[ai][bj][m][n] = __builtin_amdgcn_mfma_f32_16x16x32_bf16(Bt[n][k], At[m][k], acc[ai][bj][m][n], 0, 0, 0); __builtin_amdgcn_s_setprio(0); } while (0)
; template <class Epi, class Sched, bool HALFN = false>
; __device__ __forceinline__ void gemm_phase(LAS unsigned char* lds, const Gemm g, const Sched& S, const Epi& E, int wave_s) {
;     ...
;             PG8_LDB(B0, 0, 0); if (!HALFN) PG8_LDB(B1, 0, 1); PG8_SCHED; PG8_LDA(At, 0, 0); PG8_STAGE(PG8_SA(1, 1), a1 + hstep, voffA);
;             PG8_WAIT_V(8); PG8_WAIT_L(0); PG8_BAR; PG8_MMA(0, 0, At, B0); if (!HALFN) PG8_MMA(0, 1, At, B1); PG8_BAR; PG8_SCHED;
;             PG8_LDA(At, 0, 1); PG8_STAGE(PG8_SB(0, 0), b2, voffB); PG8_STAGE(PG8_SB(0, 1), b2 + bh1, voffB); PG8_STAGE(PG8_SA(0, 0), a2, voffA);
;             PG8_WAIT_V(8); PG8_WAIT_L(0); PG8_BAR; PG8_MMA(1, 0, At, B0); if (!HALFN) PG8_MMA(1, 1, At, B1); PG8_BAR; PG8_SCHED;
;             PG8_LDB(B0, 1, 0); if (!HALFN) PG8_LDB(B1, 1, 1); PG8_SCHED; PG8_LDA(At, 1, 0); PG8_STAGE(PG8_SA(0, 1), a2 + hstep, voffA);
;             PG8_WAIT_V(8); PG8_WAIT_L(0); PG8_BAR; PG8_MMA(0, 0, At, B0); if (!HALFN) PG8_MMA(0, 1, At, B1); PG8_BAR; PG8_SCHED;
;             PG8_LDA(At, 1, 1); PG8_STAGE(PG8_SB(1, 0), b3, voffB); PG8_STAGE(PG8_SB(1, 1), b3 + bh1, voffB); PG8_STAGE(PG8_SA(1, 0), a3, voffA);
;             PG8_WAIT_V(8); PG8_WAIT_L(0); PG8_BAR; PG8_MMA(1, 0, At, B0); if (!HALFN) PG8_MMA(1, 1, At, B1); PG8_BAR; PG8_SCHED;
	s_setprio 1
	s_waitcnt lgkmcnt(0)
	v_mfma_f32_16x16x32_bf16 v[86:89], v[54:57], v[208:211], v[86:89]
	v_mfma_f32_16x16x32_bf16 v[90:93], v[190:193], v[208:211], v[90:93]
	v_mfma_f32_16x16x32_bf16 v[94:97], v[54:57], v[220:223], v[94:97]
	v_mfma_f32_16x16x32_bf16 v[62:65], v[190:193], v[220:223], v[62:65]
	v_mfma_f32_16x16x32_bf16 v[66:69], v[54:57], v[228:231], v[66:69]
	v_mfma_f32_16x16x32_bf16 v[70:73], v[190:193], v[228:231], v[70:73]
	v_mfma_f32_16x16x32_bf16 v[74:77], v[54:57], v[236:239], v[74:77]
	v_mfma_f32_16x16x32_bf16 v[78:81], v[190:193], v[236:239], v[78:81]
	v_mfma_f32_16x16x32_bf16 v[86:89], v[58:61], v[216:219], v[86:89]
	v_mfma_f32_16x16x32_bf16 v[90:93], v[194:197], v[216:219], v[90:93]
	v_mfma_f32_16x16x32_bf16 v[94:97], v[58:61], v[224:227], v[94:97]
	v_mfma_f32_16x16x32_bf16 v[62:65], v[194:197], v[224:227], v[62:65]
	v_mfma_f32_16x16x32_bf16 v[66:69], v[58:61], v[232:235], v[66:69]
	v_mfma_f32_16x16x32_bf16 v[70:73], v[194:197], v[232:235], v[70:73]
	v_mfma_f32_16x16x32_bf16 v[74:77], v[58:61], v[240:243], v[74:77]
	v_mfma_f32_16x16x32_bf16 v[78:81], v[194:197], v[240:243], v[78:81]
	s_setprio 0
	s_barrier
	s_mov_b64 s[74:75], 0x180
	s_add_i32 s36, s29, s41
	v_lshl_add_u64 v[98:99], v[36:37], 0, s[74:75]
	s_mov_b32 m0, s36
	s_add_i32 s29, s36, 0x2000
	ds_read_b128 v[208:211], v176 offset:49152
	ds_read_b128 v[216:219], v176 offset:50176
	ds_read_b128 v[220:223], v176 offset:51200
	ds_read_b128 v[224:227], v176 offset:52224
	ds_read_b128 v[228:231], v176 offset:53248
	ds_read_b128 v[232:235], v176 offset:54272
	ds_read_b128 v[236:239], v176 offset:55296
	ds_read_b128 v[240:243], v176 offset:56320
	global_load_lds_dwordx4 v[98:99], off
	v_lshl_add_u64 v[174:175], v[38:39], 0, s[74:75]
	s_mov_b32 m0, s29
	s_nop 0
	global_load_lds_dwordx4 v[174:175], off
	s_mov_b32 m0, s64
	s_nop 0
	global_load_lds_dwordx4 v[98:99], off
	s_mov_b32 m0, s65
	v_lshl_add_u64 v[98:99], v[40:41], 0, s[74:75]
	global_load_lds_dwordx4 v[174:175], off
	s_mov_b32 m0, s59
	s_nop 0
	global_load_lds_dwordx4 v[98:99], off
	v_lshl_add_u64 v[98:99], v[42:43], 0, s[74:75]
	s_mov_b32 m0, s62
	s_nop 0
	global_load_lds_dwordx4 v[98:99], off
	s_waitcnt vmcnt(8)
	s_waitcnt lgkmcnt(0)
	s_barrier
	s_setprio 1
	s_waitcnt lgkmcnt(0)
	v_mfma_f32_16x16x32_bf16 v[82:85], v[190:193], v[208:211], v[82:85]
	v_mfma_f32_16x16x32_bf16 v[46:49], v[54:57], v[236:239], v[46:49]
	v_mfma_f32_16x16x32_bf16 v[50:53], v[190:193], v[236:239], v[50:53]
	v_mfma_f32_16x16x32_bf16 v[212:215], v[54:57], v[208:211], v[212:215]
	v_mfma_f32_16x16x32_bf16 v[82:85], v[194:197], v[216:219], v[82:85]
	v_mfma_f32_16x16x32_bf16 v[170:173], v[54:57], v[220:223], v[170:173]
	v_mfma_f32_16x16x32_bf16 v[178:181], v[190:193], v[220:223], v[178:181]
	v_mfma_f32_16x16x32_bf16 v[182:185], v[54:57], v[228:231], v[182:185]
	v_mfma_f32_16x16x32_bf16 v[186:189], v[190:193], v[228:231], v[186:189]
	v_mfma_f32_16x16x32_bf16 v[46:49], v[58:61], v[240:243], v[46:49]
	v_mfma_f32_16x16x32_bf16 v[50:53], v[194:197], v[240:243], v[50:53]
	v_mfma_f32_16x16x32_bf16 v[212:215], v[58:61], v[216:219], v[212:215]
	v_mfma_f32_16x16x32_bf16 v[170:173], v[58:61], v[224:227], v[170:173]
	v_mfma_f32_16x16x32_bf16 v[178:181], v[194:197], v[224:227], v[178:181]
	v_mfma_f32_16x16x32_bf16 v[182:185], v[58:61], v[232:235], v[182:185]
	v_mfma_f32_16x16x32_bf16 v[186:189], v[194:197], v[232:235], v[186:189]
	s_setprio 0
	s_barrier
	ds_read_b128 v[54:57], v44
	ds_read_b128 v[58:61], v44 offset:1024
	ds_read_b128 v[190:193], v44 offset:2048
	ds_read_b128 v[194:197], v44 offset:3072
	s_add_u32 s74, s34, 0x20180
	s_addc_u32 s75, s35, 0
	s_mov_b32 m0, s52
	v_lshl_add_u64 v[98:99], s[74:75], 0, v[100:101]
	ds_read_b128 v[208:211], v176
	ds_read_b128 v[216:219], v176 offset:1024
	ds_read_b128 v[220:223], v176 offset:2048
	ds_read_b128 v[224:227], v176 offset:3072
	ds_read_b128 v[228:231], v176 offset:4096
	ds_read_b128 v[232:235], v176 offset:5120
	ds_read_b128 v[236:239], v176 offset:6144
	ds_read_b128 v[240:243], v176 offset:7168
	global_load_lds_dwordx4 v[98:99], off
	v_lshl_add_u64 v[98:99], s[74:75], 0, v[102:103]
	s_mov_b32 m0, s21
	s_nop 0
	global_load_lds_dwordx4 v[98:99], off
	s_waitcnt vmcnt(8)
	s_waitcnt lgkmcnt(0)
	s_barrier
	s_setprio 1
	s_waitcnt lgkmcnt(0)
	v_mfma_f32_16x16x32_bf16 v[86:89], v[54:57], v[208:211], v[86:89]
	v_mfma_f32_16x16x32_bf16 v[90:93], v[190:193], v[208:211], v[90:93]
	v_mfma_f32_16x16x32_bf16 v[94:97], v[54:57], v[220:223], v[94:97]
	v_mfma_f32_16x16x32_bf16 v[62:65], v[190:193], v[220:223], v[62:65]
	v_mfma_f32_16x16x32_bf16 v[66:69], v[54:57], v[228:231], v[66:69]
	v_mfma_f32_16x16x32_bf16 v[70:73], v[190:193], v[228:231], v[70:73]
	v_mfma_f32_16x16x32_bf16 v[74:77], v[54:57], v[236:239], v[74:77]
	v_mfma_f32_16x16x32_bf16 v[78:81], v[190:193], v[236:239], v[78:81]
	v_mfma_f32_16x16x32_bf16 v[86:89], v[58:61], v[216:219], v[86:89]
	v_mfma_f32_16x16x32_bf16 v[90:93], v[194:197], v[216:219], v[90:93]
	v_mfma_f32_16x16x32_bf16 v[94:97], v[58:61], v[224:227], v[94:97]
	v_mfma_f32_16x16x32_bf16 v[62:65], v[194:197], v[224:227], v[62:65]
	v_mfma_f32_16x16x32_bf16 v[66:69], v[58:61], v[232:235], v[66:69]
	v_mfma_f32_16x16x32_bf16 v[70:73], v[194:197], v[232:235], v[70:73]
	v_mfma_f32_16x16x32_bf16 v[74:77], v[58:61], v[240:243], v[74:77]
	v_mfma_f32_16x16x32_bf16 v[78:81], v[194:197], v[240:243], v[78:81]
	s_setprio 0
	s_barrier
; #define PG8_STAGE(bufoff, gbase, voff) do { _Pragma("unroll") for (int _i = 0; _i < 2; ++_i) \
;         __builtin_amdgcn_global_load_lds((const unsigned*)((const char*)(gbase) + (voff)[_i]), (LAS unsigned*)(lds + (bufoff) + ldsw + _i * 8192), 16, 0, 0); } while (0)
; #define PG8_LDA(dst, b, h) do { _Pragma("unroll") for (int m = 0; m < 4; ++m) _Pragma("unroll") for (int k = 0; k < 2; ++k) dst[m][k] = *(const LAS bf16x8*)(lds + PG8_SA(b, h) + aoff + m * 2048 + k * 1024); } while (0)
; #define PG8_LDB(dst, b, h) do { _Pragma("unroll") for (int n = 0; n < 2; ++n) _Pragma("unroll") for (int k = 0; k < 2; ++k) dst[n][k] = *(const LAS bf16x8*)(lds + PG8_SB(b, h) + boff + n * 2048 + k * 1024); } while (0)
; #define PG8_MMA(ai, bj, At, Bt) do { __builtin_amdgcn_s_setprio(1); _Pragma("unroll") for (int m = 0; m < 4; ++m) _Pragma("unroll") for (int n = 0; n < 2; ++n) _Pragma("unroll") for (int k = 0; k < 2; ++k) \
;         acc[ai][bj][m][n] = __builtin_amdgcn_mfma_f32_16x16x32_bf16(Bt[n][k], At[m][k], acc[ai][bj][m][n], 0, 0, 0); __builtin_amdgcn_s_setprio(0); } while (0)
; template <class Epi, class Sched, bool HALFN = false>
; __device__ __forceinline__ void gemm_phase(LAS unsigned char* lds, const Gemm g, const Sched& S, const Epi& E, int wave_s) {
;     ...
;             PG8_LDB(B0, 0, 0); if (!HALFN) PG8_LDB(B1, 0, 1); PG8_SCHED; PG8_LDA(At, 0, 0); PG8_STAGE(PG8_SA(1, 1), a1 + hstep, voffA);
;             PG8_WAIT_V(8); PG8_WAIT_L(0); PG8_BAR; PG8_MMA(0, 0, At, B0); if (!HALFN) PG8_MMA(0, 1, At, B1); PG8_BAR; PG8_SCHED;
;             PG8_LDA(At, 0, 1); PG8_STAGE(PG8_SB(0, 0), b2, voffB); PG8_STAGE(PG8_SB(0, 1), b2 + bh1, voffB); PG8_STAGE(PG8_SA(0, 0), a2, voffA);
;             PG8_WAIT_V(8); PG8_WAIT_L(0); PG8_BAR; PG8_MMA(1, 0, At, B0); if (!HALFN) PG8_MMA(1, 1, At, B1); PG8_BAR; PG8_SCHED;
;             PG8_LDB(B0, 1, 0); if (!HALFN) PG8_LDB(B1, 1, 1); PG8_SCHED; PG8_LDA(At, 1, 0); PG8_STAGE(PG8_SA(0, 1), a2 + hstep, voffA);
;             PG8_WAIT_V(8); PG8_WAIT_L(0); PG8_BAR; PG8_MMA(0, 0, At, B0); if (!HALFN) PG8_MMA(0, 1, At, B1); PG8_BAR; PG8_SCHED;
;             PG8_LDA(At, 1, 1); PG8_STAGE(PG8_SB(1, 0), b3, voffB); PG8_STAGE(PG8_SB(1, 1), b3 + bh1, voffB); PG8_STAGE(PG8_SA(1, 0), a3, voffA);
;             PG8_WAIT_V(8); PG8_WAIT_L(0); PG8_BAR; PG8_MMA(1, 0, At, B0); if (!HALFN) PG8_MMA(1, 1, At, B1); PG8_BAR; PG8_SCHED;
	s_mov_b64 s[74:75], 0x200
	s_mov_b32 m0, s48
	v_lshl_add_u64 v[98:99], v[36:37], 0, s[74:75]
	ds_read_b128 v[208:211], v176 offset:16384
	ds_read_b128 v[216:219], v176 offset:17408
	ds_read_b128 v[220:223], v176 offset:18432
	ds_read_b128 v[224:227], v176 offset:19456
	ds_read_b128 v[228:231], v176 offset:20480
	ds_read_b128 v[232:235], v176 offset:21504
	ds_read_b128 v[236:239], v176 offset:22528
	ds_read_b128 v[240:243], v176 offset:23552
	global_load_lds_dwordx4 v[98:99], off
	v_lshl_add_u64 v[174:175], v[38:39], 0, s[74:75]
	s_mov_b32 m0, s23
	s_nop 0
	global_load_lds_dwordx4 v[174:175], off
	s_mov_b32 m0, s47
	s_nop 0
	global_load_lds_dwordx4 v[98:99], off
	s_mov_b32 m0, s55
	v_lshl_add_u64 v[98:99], v[40:41], 0, s[74:75]
	global_load_lds_dwordx4 v[174:175], off
	s_mov_b32 m0, s31
	s_nop 0
	global_load_lds_dwordx4 v[98:99], off
	v_lshl_add_u64 v[98:99], v[42:43], 0, s[74:75]
	s_mov_b32 m0, s56
	s_nop 0
	global_load_lds_dwordx4 v[98:99], off
	s_waitcnt vmcnt(8)
	s_waitcnt lgkmcnt(0)
	s_barrier
	s_setprio 1
	s_waitcnt lgkmcnt(0)
	v_mfma_f32_16x16x32_bf16 v[82:85], v[190:193], v[208:211], v[82:85]
	v_mfma_f32_16x16x32_bf16 v[46:49], v[54:57], v[236:239], v[46:49]
	v_mfma_f32_16x16x32_bf16 v[50:53], v[190:193], v[236:239], v[50:53]
	v_mfma_f32_16x16x32_bf16 v[212:215], v[54:57], v[208:211], v[212:215]
	v_mfma_f32_16x16x32_bf16 v[82:85], v[194:197], v[216:219], v[82:85]
	v_mfma_f32_16x16x32_bf16 v[170:173], v[54:57], v[220:223], v[170:173]
	v_mfma_f32_16x16x32_bf16 v[178:181], v[190:193], v[220:223], v[178:181]
	v_mfma_f32_16x16x32_bf16 v[182:185], v[54:57], v[228:231], v[182:185]
	v_mfma_f32_16x16x32_bf16 v[186:189], v[190:193], v[228:231], v[186:189]
	v_mfma_f32_16x16x32_bf16 v[46:49], v[58:61], v[240:243], v[46:49]
	v_mfma_f32_16x16x32_bf16 v[50:53], v[194:197], v[240:243], v[50:53]
	v_mfma_f32_16x16x32_bf16 v[212:215], v[58:61], v[216:219], v[212:215]
	v_mfma_f32_16x16x32_bf16 v[170:173], v[58:61], v[224:227], v[170:173]
	v_mfma_f32_16x16x32_bf16 v[178:181], v[194:197], v[224:227], v[178:181]
	v_mfma_f32_16x16x32_bf16 v[182:185], v[58:61], v[232:235], v[182:185]
	v_mfma_f32_16x16x32_bf16 v[186:189], v[194:197], v[232:235], v[186:189]
	s_setprio 0
	s_barrier
	ds_read_b128 v[54:57], v45
	ds_read_b128 v[58:61], v45 offset:1024
	ds_read_b128 v[190:193], v45 offset:2048
	ds_read_b128 v[194:197], v45 offset:3072
	s_add_u32 s74, s34, 0x20200
	s_addc_u32 s75, s35, 0
	s_mov_b32 m0, s57
	v_lshl_add_u64 v[98:99], s[74:75], 0, v[100:101]
	ds_read_b128 v[208:211], v176 offset:32768
	ds_read_b128 v[216:219], v176 offset:33792
	ds_read_b128 v[220:223], v176 offset:34816
	ds_read_b128 v[224:227], v176 offset:35840
	ds_read_b128 v[228:231], v176 offset:36864
	ds_read_b128 v[232:235], v176 offset:37888
	ds_read_b128 v[236:239], v176 offset:38912
	ds_read_b128 v[240:243], v176 offset:39936
	global_load_lds_dwordx4 v[98:99], off
	v_lshl_add_u64 v[98:99], s[74:75], 0, v[102:103]
	s_mov_b32 m0, s58
	s_nop 0
	global_load_lds_dwordx4 v[98:99], off
	s_waitcnt vmcnt(8)
	s_waitcnt lgkmcnt(0)
	s_barrier
	s_setprio 1
	s_waitcnt lgkmcnt(0)
	v_mfma_f32_16x16x32_bf16 v[86:89], v[54:57], v[208:211], v[86:89]
	v_mfma_f32_16x16x32_bf16 v[90:93], v[190:193], v[208:211], v[90:93]
	v_mfma_f32_16x16x32_bf16 v[94:97], v[54:57], v[220:223], v[94:97]
	v_mfma_f32_16x16x32_bf16 v[62:65], v[190:193], v[220:223], v[62:65]
	v_mfma_f32_16x16x32_bf16 v[66:69], v[54:57], v[228:231], v[66:69]
	v_mfma_f32_16x16x32_bf16 v[70:73], v[190:193], v[228:231], v[70:73]
	v_mfma_f32_16x16x32_bf16 v[74:77], v[54:57], v[236:239], v[74:77]
	v_mfma_f32_16x16x32_bf16 v[78:81], v[190:193], v[236:239], v[78:81]
	v_mfma_f32_16x16x32_bf16 v[86:89], v[58:61], v[216:219], v[86:89]
	v_mfma_f32_16x16x32_bf16 v[90:93], v[194:197], v[216:219], v[90:93]
	v_mfma_f32_16x16x32_bf16 v[94:97], v[58:61], v[224:227], v[94:97]
	v_mfma_f32_16x16x32_bf16 v[62:65], v[194:197], v[224:227], v[62:65]
	v_mfma_f32_16x16x32_bf16 v[66:69], v[58:61], v[232:235], v[66:69]
	v_mfma_f32_16x16x32_bf16 v[70:73], v[194:197], v[232:235], v[70:73]
	v_mfma_f32_16x16x32_bf16 v[74:77], v[58:61], v[240:243], v[74:77]
	v_mfma_f32_16x16x32_bf16 v[78:81], v[194:197], v[240:243], v[78:81]
	s_setprio 0
	s_barrier
	s_mov_b64 s[74:75], 0x280
	s_mov_b32 m0, s36
	v_lshl_add_u64 v[98:99], v[36:37], 0, s[74:75]
	ds_read_b128 v[208:211], v176 offset:49152
	ds_read_b128 v[216:219], v176 offset:50176
	ds_read_b128 v[220:223], v176 offset:51200
	ds_read_b128 v[224:227], v176 offset:52224
	ds_read_b128 v[228:231], v176 offset:53248
	ds_read_b128 v[232:235], v176 offset:54272
	ds_read_b128 v[236:239], v176 offset:55296
	ds_read_b128 v[240:243], v176 offset:56320
	global_load_lds_dwordx4 v[98:99], off
	v_lshl_add_u64 v[174:175], v[38:39], 0, s[74:75]
	s_mov_b32 m0, s29
	s_nop 0
	global_load_lds_dwordx4 v[174:175], off
	s_mov_b32 m0, s64
	s_nop 0
	global_load_lds_dwordx4 v[98:99], off
	s_mov_b32 m0, s65
	v_lshl_add_u64 v[98:99], v[40:41], 0, s[74:75]
	global_load_lds_dwordx4 v[174:175], off
	s_mov_b32 m0, s59
	s_nop 0
	global_load_lds_dwordx4 v[98:99], off
	v_lshl_add_u64 v[98:99], v[42:43], 0, s[74:75]
	s_mov_b32 m0, s62
	s_nop 0
	global_load_lds_dwordx4 v[98:99], off
	s_waitcnt vmcnt(8)
	s_waitcnt lgkmcnt(0)
	s_barrier
; #define PG8_STAGE(bufoff, gbase, voff) do { _Pragma("unroll") for (int _i = 0; _i < 2; ++_i) \
;         __builtin_amdgcn_global_load_lds((const unsigned*)((const char*)(gbase) + (voff)[_i]), (LAS unsigned*)(lds + (bufoff) + ldsw + _i * 8192), 16, 0, 0); } while (0)
; #define PG8_LDA(dst, b, h) do { _Pragma("unroll") for (int m = 0; m < 4; ++m) _Pragma("unroll") for (int k = 0; k < 2; ++k) dst[m][k] = *(const LAS bf16x8*)(lds + PG8_SA(b, h) + aoff + m * 2048 + k * 1024); } while (0)
; #define PG8_LDB(dst, b, h) do { _Pragma("unroll") for (int n = 0; n < 2; ++n) _Pragma("unroll") for (int k = 0; k < 2; ++k) dst[n][k] = *(const LAS bf16x8*)(lds + PG8_SB(b, h) + boff + n * 2048 + k * 1024); } while (0)
; #define PG8_MMA(ai, bj, At, Bt) do { __builtin_amdgcn_s_setprio(1); _Pragma("unroll") for (int m = 0; m < 4; ++m) _Pragma("unroll") for (int n = 0; n < 2; ++n) _Pragma("unroll") for (int k = 0; k < 2; ++k) \
;         acc[ai][bj][m][n] = __builtin_amdgcn_mfma_f32_16x16x32_bf16(Bt[n][k], At[m][k], acc[ai][bj][m][n], 0, 0, 0); __builtin_amdgcn_s_setprio(0); } while (0)
; template <class Epi, class Sched, bool HALFN = false>
; __device__ __forceinline__ void gemm_phase(LAS unsigned char* lds, const Gemm g, const Sched& S, const Epi& E, int wave_s) {
;     ...
;             PG8_LDB(B0, 0, 0); if (!HALFN) PG8_LDB(B1, 0, 1); PG8_SCHED; PG8_LDA(At, 0, 0); PG8_STAGE(PG8_SA(1, 1), a1 + hstep, voffA);
;             PG8_WAIT_V(8); PG8_WAIT_L(0); PG8_BAR; PG8_MMA(0, 0, At, B0); if (!HALFN) PG8_MMA(0, 1, At, B1); PG8_BAR; PG8_SCHED;
;             PG8_LDA(At, 0, 1); PG8_STAGE(PG8_SB(0, 0), b2, voffB); PG8_STAGE(PG8_SB(0, 1), b2 + bh1, voffB); PG8_STAGE(PG8_SA(0, 0), a2, voffA);
;             PG8_WAIT_V(8); PG8_WAIT_L(0); PG8_BAR; PG8_MMA(1, 0, At, B0); if (!HALFN) PG8_MMA(1, 1, At, B1); PG8_BAR; PG8_SCHED;
;             PG8_LDB(B0, 1, 0); if (!HALFN) PG8_LDB(B1, 1, 1); PG8_SCHED; PG8_LDA(At, 1, 0); PG8_STAGE(PG8_SA(0, 1), a2 + hstep, voffA);
;             PG8_WAIT_V(8); PG8_WAIT_L(0); PG8_BAR; PG8_MMA(0, 0, At, B0); if (!HALFN) PG8_MMA(0, 1, At, B1); PG8_BAR; PG8_SCHED;
;             PG8_LDA(At, 1, 1); PG8_STAGE(PG8_SB(1, 0), b3, voffB); PG8_STAGE(PG8_SB(1, 1), b3 + bh1, voffB); PG8_STAGE(PG8_SA(1, 0), a3, voffA);
;             PG8_WAIT_V(8); PG8_WAIT_L(0); PG8_BAR; PG8_MMA(1, 0, At, B0); if (!HALFN) PG8_MMA(1, 1, At, B1); PG8_BAR; PG8_SCHED;
	s_setprio 1
	s_waitcnt lgkmcnt(0)
	v_mfma_f32_16x16x32_bf16 v[82:85], v[190:193], v[208:211], v[82:85]
	v_mfma_f32_16x16x32_bf16 v[46:49], v[54:57], v[236:239], v[46:49]
	v_mfma_f32_16x16x32_bf16 v[50:53], v[190:193], v[236:239], v[50:53]
	v_mfma_f32_16x16x32_bf16 v[212:215], v[54:57], v[208:211], v[212:215]
	v_mfma_f32_16x16x32_bf16 v[82:85], v[194:197], v[216:219], v[82:85]
	v_mfma_f32_16x16x32_bf16 v[170:173], v[54:57], v[220:223], v[170:173]
	v_mfma_f32_16x16x32_bf16 v[178:181], v[190:193], v[220:223], v[178:181]
	v_mfma_f32_16x16x32_bf16 v[182:185], v[54:57], v[228:231], v[182:185]
	v_mfma_f32_16x16x32_bf16 v[186:189], v[190:193], v[228:231], v[186:189]
	v_mfma_f32_16x16x32_bf16 v[46:49], v[58:61], v[240:243], v[46:49]
	v_mfma_f32_16x16x32_bf16 v[50:53], v[194:197], v[240:243], v[50:53]
	v_mfma_f32_16x16x32_bf16 v[212:215], v[58:61], v[216:219], v[212:215]
	v_mfma_f32_16x16x32_bf16 v[170:173], v[58:61], v[224:227], v[170:173]
	v_mfma_f32_16x16x32_bf16 v[178:181], v[194:197], v[224:227], v[178:181]
	v_mfma_f32_16x16x32_bf16 v[182:185], v[58:61], v[232:235], v[182:185]
	v_mfma_f32_16x16x32_bf16 v[186:189], v[194:197], v[232:235], v[186:189]
	s_setprio 0
	s_barrier
	ds_read_b128 v[54:57], v44
	ds_read_b128 v[58:61], v44 offset:1024
	ds_read_b128 v[190:193], v44 offset:2048
	ds_read_b128 v[194:197], v44 offset:3072
	s_add_u32 s74, s34, 0x20280
	s_addc_u32 s75, s35, 0
	s_mov_b32 m0, s52
	v_lshl_add_u64 v[98:99], s[74:75], 0, v[100:101]
	ds_read_b128 v[208:211], v176
	ds_read_b128 v[216:219], v176 offset:1024
	ds_read_b128 v[220:223], v176 offset:2048
	ds_read_b128 v[224:227], v176 offset:3072
	ds_read_b128 v[228:231], v176 offset:4096
	ds_read_b128 v[232:235], v176 offset:5120
	ds_read_b128 v[236:239], v176 offset:6144
	ds_read_b128 v[240:243], v176 offset:7168
	global_load_lds_dwordx4 v[98:99], off
	v_lshl_add_u64 v[98:99], s[74:75], 0, v[102:103]
	s_mov_b32 m0, s21
	s_nop 0
	global_load_lds_dwordx4 v[98:99], off
	s_waitcnt vmcnt(8)
	s_waitcnt lgkmcnt(0)
	s_barrier
	s_setprio 1
	s_waitcnt lgkmcnt(0)
	v_mfma_f32_16x16x32_bf16 v[86:89], v[54:57], v[208:211], v[86:89]
	v_mfma_f32_16x16x32_bf16 v[90:93], v[190:193], v[208:211], v[90:93]
	v_mfma_f32_16x16x32_bf16 v[94:97], v[54:57], v[220:223], v[94:97]
	v_mfma_f32_16x16x32_bf16 v[62:65], v[190:193], v[220:223], v[62:65]
	v_mfma_f32_16x16x32_bf16 v[66:69], v[54:57], v[228:231], v[66:69]
	v_mfma_f32_16x16x32_bf16 v[70:73], v[190:193], v[228:231], v[70:73]
	v_mfma_f32_16x16x32_bf16 v[74:77], v[54:57], v[236:239], v[74:77]
	v_mfma_f32_16x16x32_bf16 v[78:81], v[190:193], v[236:239], v[78:81]
	v_mfma_f32_16x16x32_bf16 v[86:89], v[58:61], v[216:219], v[86:89]
	v_mfma_f32_16x16x32_bf16 v[90:93], v[194:197], v[216:219], v[90:93]
	v_mfma_f32_16x16x32_bf16 v[94:97], v[58:61], v[224:227], v[94:97]
	v_mfma_f32_16x16x32_bf16 v[62:65], v[194:197], v[224:227], v[62:65]
	v_mfma_f32_16x16x32_bf16 v[66:69], v[58:61], v[232:235], v[66:69]
	v_mfma_f32_16x16x32_bf16 v[70:73], v[194:197], v[232:235], v[70:73]
	v_mfma_f32_16x16x32_bf16 v[74:77], v[58:61], v[240:243], v[74:77]
	v_mfma_f32_16x16x32_bf16 v[78:81], v[194:197], v[240:243], v[78:81]
	s_setprio 0
	s_barrier
	s_mov_b64 s[74:75], 0x300
	s_mov_b32 m0, s48
	v_lshl_add_u64 v[98:99], v[36:37], 0, s[74:75]
	ds_read_b128 v[208:211], v176 offset:16384
	ds_read_b128 v[216:219], v176 offset:17408
	ds_read_b128 v[220:223], v176 offset:18432
	ds_read_b128 v[224:227], v176 offset:19456
	ds_read_b128 v[228:231], v176 offset:20480
	ds_read_b128 v[232:235], v176 offset:21504
	ds_read_b128 v[236:239], v176 offset:22528
	ds_read_b128 v[240:243], v176 offset:23552
	global_load_lds_dwordx4 v[98:99], off
	v_lshl_add_u64 v[174:175], v[38:39], 0, s[74:75]
	s_mov_b32 m0, s23
	s_nop 0
	global_load_lds_dwordx4 v[174:175], off
	s_mov_b32 m0, s47
	s_nop 0
	global_load_lds_dwordx4 v[98:99], off
	s_mov_b32 m0, s55
	v_lshl_add_u64 v[98:99], v[40:41], 0, s[74:75]
	global_load_lds_dwordx4 v[174:175], off
	s_mov_b32 m0, s31
	s_nop 0
	global_load_lds_dwordx4 v[98:99], off
	v_lshl_add_u64 v[98:99], v[42:43], 0, s[74:75]
	s_mov_b32 m0, s56
	s_nop 0
	global_load_lds_dwordx4 v[98:99], off
	s_waitcnt vmcnt(8)
	s_waitcnt lgkmcnt(0)
	s_barrier
	s_setprio 1
	s_waitcnt lgkmcnt(0)
	v_mfma_f32_16x16x32_bf16 v[82:85], v[190:193], v[208:211], v[82:85]
	v_mfma_f32_16x16x32_bf16 v[46:49], v[54:57], v[236:239], v[46:49]
	v_mfma_f32_16x16x32_bf16 v[50:53], v[190:193], v[236:239], v[50:53]
	v_mfma_f32_16x16x32_bf16 v[212:215], v[54:57], v[208:211], v[212:215]
	v_mfma_f32_16x16x32_bf16 v[82:85], v[194:197], v[216:219], v[82:85]
	v_mfma_f32_16x16x32_bf16 v[170:173], v[54:57], v[220:223], v[170:173]
	v_mfma_f32_16x16x32_bf16 v[178:181], v[190:193], v[220:223], v[178:181]
	v_mfma_f32_16x16x32_bf16 v[182:185], v[54:57], v[228:231], v[182:185]
	v_mfma_f32_16x16x32_bf16 v[186:189], v[190:193], v[228:231], v[186:189]
	v_mfma_f32_16x16x32_bf16 v[46:49], v[58:61], v[240:243], v[46:49]
	v_mfma_f32_16x16x32_bf16 v[50:53], v[194:197], v[240:243], v[50:53]
	v_mfma_f32_16x16x32_bf16 v[212:215], v[58:61], v[216:219], v[212:215]
	v_mfma_f32_16x16x32_bf16 v[170:173], v[58:61], v[224:227], v[170:173]
	v_mfma_f32_16x16x32_bf16 v[178:181], v[194:197], v[224:227], v[178:181]
	v_mfma_f32_16x16x32_bf16 v[182:185], v[58:61], v[232:235], v[182:185]
	v_mfma_f32_16x16x32_bf16 v[186:189], v[194:197], v[232:235], v[186:189]
	s_setprio 0
	s_barrier
; #define PG8_STAGE(bufoff, gbase, voff) do { _Pragma("unroll") for (int _i = 0; _i < 2; ++_i) \
;         __builtin_amdgcn_global_load_lds((const unsigned*)((const char*)(gbase) + (voff)[_i]), (LAS unsigned*)(lds + (bufoff) + ldsw + _i * 8192), 16, 0, 0); } while (0)
; #define PG8_LDA(dst, b, h) do { _Pragma("unroll") for (int m = 0; m < 4; ++m) _Pragma("unroll") for (int k = 0; k < 2; ++k) dst[m][k] = *(const LAS bf16x8*)(lds + PG8_SA(b, h) + aoff + m * 2048 + k * 1024); } while (0)
; #define PG8_LDB(dst, b, h) do { _Pragma("unroll") for (int n = 0; n < 2; ++n) _Pragma("unroll") for (int k = 0; k < 2; ++k) dst[n][k] = *(const LAS bf16x8*)(lds + PG8_SB(b, h) + boff + n * 2048 + k * 1024); } while (0)
; #define PG8_MMA(ai, bj, At, Bt) do { __builtin_amdgcn_s_setprio(1); _Pragma("unroll") for (int m = 0; m < 4; ++m) _Pragma("unroll") for (int n = 0; n < 2; ++n) _Pragma("unroll") for (int k = 0; k < 2; ++k) \
;         acc[ai][bj][m][n] = __builtin_amdgcn_mfma_f32_16x16x32_bf16(Bt[n][k], At[m][k], acc[ai][bj][m][n], 0, 0, 0); __builtin_amdgcn_s_setprio(0); } while (0)
; template <class Epi, class Sched, bool HALFN = false>
; __device__ __forceinline__ void gemm_phase(LAS unsigned char* lds, const Gemm g, const Sched& S, const Epi& E, int wave_s) {
;     ...
;             PG8_LDB(B0, 0, 0); if (!HALFN) PG8_LDB(B1, 0, 1); PG8_SCHED; PG8_LDA(At, 0, 0); PG8_STAGE(PG8_SA(1, 1), a1 + hstep, voffA);
;             PG8_WAIT_V(8); PG8_WAIT_L(0); PG8_BAR; PG8_MMA(0, 0, At, B0); if (!HALFN) PG8_MMA(0, 1, At, B1); PG8_BAR; PG8_SCHED;
;             PG8_LDA(At, 0, 1); PG8_STAGE(PG8_SB(0, 0), b2, voffB); PG8_STAGE(PG8_SB(0, 1), b2 + bh1, voffB); PG8_STAGE(PG8_SA(0, 0), a2, voffA);
;             PG8_WAIT_V(8); PG8_WAIT_L(0); PG8_BAR; PG8_MMA(1, 0, At, B0); if (!HALFN) PG8_MMA(1, 1, At, B1); PG8_BAR; PG8_SCHED;
;             PG8_LDB(B0, 1, 0); if (!HALFN) PG8_LDB(B1, 1, 1); PG8_SCHED; PG8_LDA(At, 1, 0); PG8_STAGE(PG8_SA(0, 1), a2 + hstep, voffA);
;             PG8_WAIT_V(8); PG8_WAIT_L(0); PG8_BAR; PG8_MMA(0, 0, At, B0); if (!HALFN) PG8_MMA(0, 1, At, B1); PG8_BAR; PG8_SCHED;
;             PG8_LDA(At, 1, 1); PG8_STAGE(PG8_SB(1, 0), b3, voffB); PG8_STAGE(PG8_SB(1, 1), b3 + bh1, voffB); PG8_STAGE(PG8_SA(1, 0), a3, voffA);
;             PG8_WAIT_V(8); PG8_WAIT_L(0); PG8_BAR; PG8_MMA(1, 0, At, B0); if (!HALFN) PG8_MMA(1, 1, At, B1); PG8_BAR; PG8_SCHED;
	ds_read_b128 v[54:57], v45
	ds_read_b128 v[58:61], v45 offset:1024
	ds_read_b128 v[190:193], v45 offset:2048
	ds_read_b128 v[194:197], v45 offset:3072
	s_add_u32 s74, s34, 0x20300
	s_addc_u32 s75, s35, 0
	s_mov_b32 m0, s57
	v_lshl_add_u64 v[98:99], s[74:75], 0, v[100:101]
	ds_read_b128 v[208:211], v176 offset:32768
	ds_read_b128 v[216:219], v176 offset:33792
	ds_read_b128 v[220:223], v176 offset:34816
	ds_read_b128 v[224:227], v176 offset:35840
	ds_read_b128 v[228:231], v176 offset:36864
	ds_read_b128 v[232:235], v176 offset:37888
	ds_read_b128 v[236:239], v176 offset:38912
	ds_read_b128 v[240:243], v176 offset:39936
	global_load_lds_dwordx4 v[98:99], off
	v_lshl_add_u64 v[98:99], s[74:75], 0, v[102:103]
	s_mov_b32 m0, s58
	s_nop 0
	global_load_lds_dwordx4 v[98:99], off
	s_waitcnt vmcnt(8)
	s_waitcnt lgkmcnt(0)
	s_barrier
	s_setprio 1
	s_waitcnt lgkmcnt(0)
	v_mfma_f32_16x16x32_bf16 v[86:89], v[54:57], v[208:211], v[86:89]
	v_mfma_f32_16x16x32_bf16 v[90:93], v[190:193], v[208:211], v[90:93]
	v_mfma_f32_16x16x32_bf16 v[94:97], v[54:57], v[220:223], v[94:97]
	v_mfma_f32_16x16x32_bf16 v[62:65], v[190:193], v[220:223], v[62:65]
	v_mfma_f32_16x16x32_bf16 v[66:69], v[54:57], v[228:231], v[66:69]
	v_mfma_f32_16x16x32_bf16 v[70:73], v[190:193], v[228:231], v[70:73]
	v_mfma_f32_16x16x32_bf16 v[74:77], v[54:57], v[236:239], v[74:77]
	v_mfma_f32_16x16x32_bf16 v[78:81], v[190:193], v[236:239], v[78:81]
	v_mfma_f32_16x16x32_bf16 v[86:89], v[58:61], v[216:219], v[86:89]
	v_mfma_f32_16x16x32_bf16 v[90:93], v[194:197], v[216:219], v[90:93]
	v_mfma_f32_16x16x32_bf16 v[94:97], v[58:61], v[224:227], v[94:97]
	v_mfma_f32_16x16x32_bf16 v[62:65], v[194:197], v[224:227], v[62:65]
	v_mfma_f32_16x16x32_bf16 v[66:69], v[58:61], v[232:235], v[66:69]
	v_mfma_f32_16x16x32_bf16 v[70:73], v[194:197], v[232:235], v[70:73]
	v_mfma_f32_16x16x32_bf16 v[74:77], v[58:61], v[240:243], v[74:77]
	v_mfma_f32_16x16x32_bf16 v[78:81], v[194:197], v[240:243], v[78:81]
	s_setprio 0
	s_barrier
	s_mov_b64 s[74:75], 0x380
	s_mov_b32 m0, s36
	v_lshl_add_u64 v[36:37], v[36:37], 0, s[74:75]
	ds_read_b128 v[208:211], v176 offset:49152
	ds_read_b128 v[216:219], v176 offset:50176
	ds_read_b128 v[220:223], v176 offset:51200
	ds_read_b128 v[224:227], v176 offset:52224
	ds_read_b128 v[228:231], v176 offset:53248
	ds_read_b128 v[232:235], v176 offset:54272
	ds_read_b128 v[236:239], v176 offset:55296
	ds_read_b128 v[240:243], v176 offset:56320
	global_load_lds_dwordx4 v[36:37], off
	v_lshl_add_u64 v[38:39], v[38:39], 0, s[74:75]
	s_mov_b32 m0, s29
	s_nop 0
	global_load_lds_dwordx4 v[38:39], off
	s_mov_b32 m0, s64
	s_nop 0
	global_load_lds_dwordx4 v[36:37], off
	s_mov_b32 m0, s65
	v_lshl_add_u64 v[36:37], v[40:41], 0, s[74:75]
	global_load_lds_dwordx4 v[38:39], off
	s_mov_b32 m0, s59
	s_nop 0
	global_load_lds_dwordx4 v[36:37], off
	v_lshl_add_u64 v[36:37], v[42:43], 0, s[74:75]
	s_mov_b32 m0, s62
	s_nop 0
	global_load_lds_dwordx4 v[36:37], off
	s_waitcnt vmcnt(8)
	s_waitcnt lgkmcnt(0)
	s_barrier
	s_setprio 1
	s_waitcnt lgkmcnt(0)
	v_mfma_f32_16x16x32_bf16 v[36:39], v[54:57], v[208:211], v[212:215]
	v_mfma_f32_16x16x32_bf16 v[40:43], v[190:193], v[208:211], v[82:85]
	v_mfma_f32_16x16x32_bf16 v[82:85], v[54:57], v[220:223], v[170:173]
	v_mfma_f32_16x16x32_bf16 v[46:49], v[54:57], v[236:239], v[46:49]
	v_mfma_f32_16x16x32_bf16 v[50:53], v[190:193], v[236:239], v[50:53]
	v_mfma_f32_16x16x32_bf16 v[36:39], v[58:61], v[216:219], v[36:39]
	v_mfma_f32_16x16x32_bf16 v[40:43], v[194:197], v[216:219], v[40:43]
	v_mfma_f32_16x16x32_bf16 v[82:85], v[58:61], v[224:227], v[82:85]
	v_mfma_f32_16x16x32_bf16 v[170:173], v[190:193], v[220:223], v[178:181]
	v_mfma_f32_16x16x32_bf16 v[178:181], v[54:57], v[228:231], v[182:185]
	v_mfma_f32_16x16x32_bf16 v[182:185], v[190:193], v[228:231], v[186:189]
	v_mfma_f32_16x16x32_bf16 v[46:49], v[58:61], v[240:243], v[46:49]
	v_mfma_f32_16x16x32_bf16 v[50:53], v[194:197], v[240:243], v[50:53]
	v_mfma_f32_16x16x32_bf16 v[170:173], v[194:197], v[224:227], v[170:173]
	v_mfma_f32_16x16x32_bf16 v[178:181], v[58:61], v[232:235], v[178:181]
	v_mfma_f32_16x16x32_bf16 v[182:185], v[194:197], v[232:235], v[182:185]
	s_setprio 0
	s_barrier
	ds_read_b128 v[54:57], v44
	ds_read_b128 v[58:61], v44 offset:1024
	ds_read_b128 v[186:189], v44 offset:2048
	ds_read_b128 v[190:193], v44 offset:3072
	s_add_u32 s34, s34, 0x20380
	s_addc_u32 s35, s35, 0
	s_mov_b32 m0, s52
	v_lshl_add_u64 v[98:99], s[34:35], 0, v[100:101]
	ds_read_b128 v[194:197], v176
	ds_read_b128 v[208:211], v176 offset:1024
	ds_read_b128 v[212:215], v176 offset:2048
	ds_read_b128 v[216:219], v176 offset:3072
	ds_read_b128 v[220:223], v176 offset:4096
	ds_read_b128 v[224:227], v176 offset:5120
	ds_read_b128 v[228:231], v176 offset:6144
	ds_read_b128 v[232:235], v176 offset:7168
	global_load_lds_dwordx4 v[98:99], off
	v_lshl_add_u64 v[98:99], s[34:35], 0, v[102:103]
	s_mov_b32 m0, s21
	s_nop 0
	global_load_lds_dwordx4 v[98:99], off
	s_waitcnt vmcnt(8)
	s_waitcnt lgkmcnt(0)
	s_barrier
	s_setprio 1
	s_waitcnt lgkmcnt(0)
	v_mfma_f32_16x16x32_bf16 v[86:89], v[54:57], v[194:197], v[86:89]
	v_mfma_f32_16x16x32_bf16 v[90:93], v[186:189], v[194:197], v[90:93]
	v_mfma_f32_16x16x32_bf16 v[62:65], v[186:189], v[212:215], v[62:65]
	v_mfma_f32_16x16x32_bf16 v[66:69], v[54:57], v[220:223], v[66:69]
	v_mfma_f32_16x16x32_bf16 v[70:73], v[186:189], v[220:223], v[70:73]
	v_mfma_f32_16x16x32_bf16 v[74:77], v[54:57], v[228:231], v[74:77]
	v_mfma_f32_16x16x32_bf16 v[86:89], v[58:61], v[208:211], v[86:89]
	v_mfma_f32_16x16x32_bf16 v[90:93], v[190:193], v[208:211], v[90:93]
	v_mfma_f32_16x16x32_bf16 v[94:97], v[54:57], v[212:215], v[94:97]
	v_mfma_f32_16x16x32_bf16 v[62:65], v[190:193], v[216:219], v[62:65]
	v_mfma_f32_16x16x32_bf16 v[66:69], v[58:61], v[224:227], v[66:69]
	v_mfma_f32_16x16x32_bf16 v[70:73], v[190:193], v[224:227], v[70:73]
	v_mfma_f32_16x16x32_bf16 v[208:211], v[58:61], v[232:235], v[74:77]
	v_mfma_f32_16x16x32_bf16 v[74:77], v[186:189], v[228:231], v[78:81]
	v_mfma_f32_16x16x32_bf16 v[194:197], v[58:61], v[216:219], v[94:97]
	v_mfma_f32_16x16x32_bf16 v[212:215], v[190:193], v[232:235], v[74:77]
	s_setprio 0
	s_barrier
; #define PG8_STAGE(bufoff, gbase, voff) do { _Pragma("unroll") for (int _i = 0; _i < 2; ++_i) \
;         __builtin_amdgcn_global_load_lds((const unsigned*)((const char*)(gbase) + (voff)[_i]), (LAS unsigned*)(lds + (bufoff) + ldsw + _i * 8192), 16, 0, 0); } while (0)
; #define PG8_WAIT_V(n) asm volatile("s_waitcnt vmcnt(" #n ")" ::: "memory")
; #define PG8_WAIT_L(n) asm volatile("s_waitcnt lgkmcnt(" #n ")" ::: "memory")
; #define PG8_BAR __builtin_amdgcn_s_barrier()
; template <class Epi, class Sched, bool HALFN = false>
; __device__ __forceinline__ void gemm_phase(LAS unsigned char* lds, const Gemm g, const Sched& S, const Epi& E, int wave_s) {
;     ...
;         const char* nA = has_next ? (const char*)g.A + (size_t)nxt.z * g.zA * 2 + (size_t)nxt.pm * tstep : cA; const char* nB = has_next ? (const char*)g.Bt + (size_t)nxt.z * g.zB * 2 + (size_t)nxt.pn * (HALFN ? hstep : tstep) : cB;
;         for (int t = 0; t < nt; t += 2) {
;             const bool last = (t == nt - 2);
;             const char* a1 = cA + (size_t)(t + 1) * kstep;
;             const char* a2 = last ? nA : cA + (size_t)(t + 2) * kstep; const char* b2 = last ? nB : cB + (size_t)(t + 2) * kstep;
;             const char* a3 = a2 + kstep; const char* b3 = b2 + kstep;
;             PG8_LDB(B0, 0, 0); if (!HALFN) PG8_LDB(B1, 0, 1); PG8_SCHED; PG8_LDA(At, 0, 0); PG8_STAGE(PG8_SA(1, 1), a1 + hstep, voffA);
;             PG8_WAIT_V(8); PG8_WAIT_L(0); PG8_BAR; PG8_MMA(0, 0, At, B0); if (!HALFN) PG8_MMA(0, 1, At, B1); PG8_BAR; PG8_SCHED;
;             PG8_LDA(At, 0, 1); PG8_STAGE(PG8_SB(0, 0), b2, voffB); PG8_STAGE(PG8_SB(0, 1), b2 + bh1, voffB); PG8_STAGE(PG8_SA(0, 0), a2, voffA);
;             PG8_WAIT_V(8); PG8_WAIT_L(0); PG8_BAR; PG8_MMA(1, 0, At, B0); if (!HALFN) PG8_MMA(1, 1, At, B1); PG8_BAR; PG8_SCHED;
;             PG8_LDB(B0, 1, 0); if (!HALFN) PG8_LDB(B1, 1, 1); PG8_SCHED; PG8_LDA(At, 1, 0); PG8_STAGE(PG8_SA(0, 1), a2 + hstep, voffA);
;             PG8_WAIT_V(8); PG8_WAIT_L(0); PG8_BAR; PG8_MMA(0, 0, At, B0); if (!HALFN) PG8_MMA(0, 1, At, B1); PG8_BAR; PG8_SCHED;
;             PG8_LDA(At, 1, 1); PG8_STAGE(PG8_SB(1, 0), b3, voffB); PG8_STAGE(PG8_SB(1, 1), b3 + bh1, voffB); PG8_STAGE(PG8_SA(1, 0), a3, voffA);
;             PG8_WAIT_V(8); PG8_WAIT_L(0); PG8_BAR; PG8_MMA(1, 0, At, B0); if (!HALFN) PG8_MMA(1, 1, At, B1); PG8_BAR; PG8_SCHED;
;         }
;         if (wr == 0) PG8_BAR;
	s_mov_b32 m0, s48
	v_lshl_add_u64 v[174:175], s[4:5], 0, v[18:19]
	s_nop 1
	ds_read_b128 v[74:77], v176 offset:16384
	ds_read_b128 v[78:81], v176 offset:17408
	ds_read_b128 v[94:97], v176 offset:18432
	ds_read_b128 v[216:219], v176 offset:19456
	ds_read_b128 v[220:223], v176 offset:20480
	ds_read_b128 v[224:227], v176 offset:21504
	ds_read_b128 v[228:231], v176 offset:22528
	ds_read_b128 v[232:235], v176 offset:23552
	global_load_lds_dwordx4 v[174:175], off
	v_lshl_add_u64 v[198:199], s[4:5], 0, v[104:105]
	s_mov_b32 m0, s23
	v_lshl_add_u64 v[202:203], s[24:25], 0, v[100:101]
	global_load_lds_dwordx4 v[198:199], off
	s_mov_b32 m0, s47
	v_lshl_add_u64 v[248:249], s[24:25], 0, v[102:103]
	global_load_lds_dwordx4 v[174:175], off
	s_mov_b32 m0, s55
	s_nop 0
	global_load_lds_dwordx4 v[198:199], off
	s_mov_b32 m0, s31
	s_nop 0
	global_load_lds_dwordx4 v[202:203], off
	s_mov_b32 m0, s56
	s_nop 0
	global_load_lds_dwordx4 v[248:249], off
	s_waitcnt vmcnt(8)
	s_waitcnt lgkmcnt(0)
	s_barrier
	s_setprio 1
	s_waitcnt lgkmcnt(0)
	v_mfma_f32_16x16x32_bf16 v[36:39], v[54:57], v[74:77], v[36:39]
	v_mfma_f32_16x16x32_bf16 v[40:43], v[186:189], v[74:77], v[40:43]
	v_mfma_f32_16x16x32_bf16 v[74:77], v[54:57], v[94:97], v[82:85]
	v_mfma_f32_16x16x32_bf16 v[236:239], v[58:61], v[216:219], v[74:77]
	v_mfma_f32_16x16x32_bf16 v[74:77], v[186:189], v[94:97], v[170:173]
	v_mfma_f32_16x16x32_bf16 v[170:173], v[190:193], v[216:219], v[74:77]
	v_mfma_f32_16x16x32_bf16 v[74:77], v[54:57], v[220:223], v[178:181]
	v_mfma_f32_16x16x32_bf16 v[46:49], v[54:57], v[228:231], v[46:49]
	v_mfma_f32_16x16x32_bf16 v[36:39], v[58:61], v[78:81], v[36:39]
	v_mfma_f32_16x16x32_bf16 v[40:43], v[190:193], v[78:81], v[40:43]
	v_mfma_f32_16x16x32_bf16 v[178:181], v[58:61], v[224:227], v[74:77]
	v_mfma_f32_16x16x32_bf16 v[74:77], v[186:189], v[220:223], v[182:185]
	v_mfma_f32_16x16x32_bf16 v[216:219], v[58:61], v[232:235], v[46:49]
	v_mfma_f32_16x16x32_bf16 v[46:49], v[186:189], v[228:231], v[50:53]
	v_mfma_f32_16x16x32_bf16 v[182:185], v[190:193], v[224:227], v[74:77]
	v_mfma_f32_16x16x32_bf16 v[186:189], v[190:193], v[232:235], v[46:49]
	s_setprio 0
	s_barrier
	ds_read_b128 v[190:193], v45
	ds_read_b128 v[220:223], v45 offset:1024
	ds_read_b128 v[224:227], v45 offset:2048
	ds_read_b128 v[228:231], v45 offset:3072
	s_add_u32 s4, s24, 0x20000
	s_addc_u32 s5, s25, 0
	s_mov_b32 m0, s57
	v_lshl_add_u64 v[60:61], s[4:5], 0, v[100:101]
	ds_read_b128 v[44:47], v176 offset:32768
	ds_read_b128 v[48:51], v176 offset:33792
	ds_read_b128 v[52:55], v176 offset:34816
	ds_read_b128 v[56:59], v176 offset:35840
	ds_read_b128 v[74:77], v176 offset:36864
	ds_read_b128 v[232:235], v176 offset:37888
	ds_read_b128 v[240:243], v176 offset:38912
	ds_read_b128 v[244:247], v176 offset:39936
	global_load_lds_dwordx4 v[60:61], off
	v_lshl_add_u64 v[60:61], s[4:5], 0, v[102:103]
	s_mov_b32 m0, s58
	s_nop 0
	global_load_lds_dwordx4 v[60:61], off
	s_waitcnt vmcnt(8)
	s_waitcnt lgkmcnt(0)
	s_barrier
	s_setprio 1
	s_waitcnt lgkmcnt(0)
	v_mfma_f32_16x16x32_bf16 v[78:81], v[190:193], v[44:47], v[86:89]
	v_mfma_f32_16x16x32_bf16 v[44:47], v[224:227], v[44:47], v[90:93]
	v_mfma_f32_16x16x32_bf16 v[92:95], v[228:231], v[48:51], v[44:47]
	v_mfma_f32_16x16x32_bf16 v[44:47], v[190:193], v[52:55], v[194:197]
	v_mfma_f32_16x16x32_bf16 v[88:91], v[220:223], v[56:59], v[44:47]
	v_mfma_f32_16x16x32_bf16 v[44:47], v[224:227], v[52:55], v[62:65]
	v_mfma_f32_16x16x32_bf16 v[84:87], v[228:231], v[56:59], v[44:47]
	v_mfma_f32_16x16x32_bf16 v[44:47], v[190:193], v[74:77], v[66:69]
	v_mfma_f32_16x16x32_bf16 v[96:99], v[220:223], v[48:51], v[78:81]
	v_mfma_f32_16x16x32_bf16 v[80:83], v[220:223], v[232:235], v[44:47]
	v_mfma_f32_16x16x32_bf16 v[44:47], v[224:227], v[74:77], v[70:73]
	v_mfma_f32_16x16x32_bf16 v[76:79], v[228:231], v[232:235], v[44:47]
	v_mfma_f32_16x16x32_bf16 v[44:47], v[190:193], v[240:243], v[208:211]
	v_mfma_f32_16x16x32_bf16 v[72:75], v[220:223], v[244:247], v[44:47]
	v_mfma_f32_16x16x32_bf16 v[44:47], v[224:227], v[240:243], v[212:215]
	v_mfma_f32_16x16x32_bf16 v[68:71], v[228:231], v[244:247], v[44:47]
	s_setprio 0
	s_barrier
	s_mov_b32 m0, s36
	v_lshl_add_u64 v[56:57], v[174:175], 0, s[50:51]
	s_nop 2
	ds_read_b128 v[44:47], v176 offset:49152
	ds_read_b128 v[48:51], v176 offset:50176
	ds_read_b128 v[52:55], v176 offset:51200
	ds_read_b128 v[194:197], v176 offset:52224
	ds_read_b128 v[208:211], v176 offset:53248
	ds_read_b128 v[212:215], v176 offset:54272
	ds_read_b128 v[232:235], v176 offset:55296
	ds_read_b128 v[240:243], v176 offset:56320
	global_load_lds_dwordx4 v[56:57], off
	v_lshl_add_u64 v[58:59], v[198:199], 0, s[50:51]
	s_mov_b32 m0, s29
	s_nop 0
	global_load_lds_dwordx4 v[58:59], off
	s_mov_b32 m0, s64
	s_nop 0
	global_load_lds_dwordx4 v[56:57], off
	s_mov_b32 m0, s65
	v_lshl_add_u64 v[56:57], v[202:203], 0, s[50:51]
	global_load_lds_dwordx4 v[58:59], off
	s_mov_b32 m0, s59
	s_nop 0
	global_load_lds_dwordx4 v[56:57], off
	v_lshl_add_u64 v[56:57], v[248:249], 0, s[50:51]
	s_mov_b32 m0, s62
	s_nop 0
	global_load_lds_dwordx4 v[56:57], off
	s_waitcnt vmcnt(8)
	s_waitcnt lgkmcnt(0)
	s_barrier
	s_setprio 1
	s_waitcnt lgkmcnt(0)
	v_mfma_f32_16x16x32_bf16 v[36:39], v[190:193], v[44:47], v[36:39]
	v_mfma_f32_16x16x32_bf16 v[64:67], v[220:223], v[48:51], v[36:39]
	v_mfma_f32_16x16x32_bf16 v[36:39], v[224:227], v[44:47], v[40:43]
	v_mfma_f32_16x16x32_bf16 v[60:63], v[228:231], v[48:51], v[36:39]
	v_mfma_f32_16x16x32_bf16 v[36:39], v[190:193], v[52:55], v[236:239]
	v_mfma_f32_16x16x32_bf16 v[56:59], v[220:223], v[194:197], v[36:39]
	v_mfma_f32_16x16x32_bf16 v[36:39], v[224:227], v[52:55], v[170:173]
	v_mfma_f32_16x16x32_bf16 v[52:55], v[228:231], v[194:197], v[36:39]
	v_mfma_f32_16x16x32_bf16 v[36:39], v[190:193], v[208:211], v[178:181]
	v_mfma_f32_16x16x32_bf16 v[48:51], v[220:223], v[212:215], v[36:39]
	v_mfma_f32_16x16x32_bf16 v[36:39], v[224:227], v[208:211], v[182:185]
	v_mfma_f32_16x16x32_bf16 v[44:47], v[228:231], v[212:215], v[36:39]
	v_mfma_f32_16x16x32_bf16 v[36:39], v[190:193], v[232:235], v[216:219]
	v_mfma_f32_16x16x32_bf16 v[40:43], v[220:223], v[240:243], v[36:39]
	v_mfma_f32_16x16x32_bf16 v[36:39], v[224:227], v[232:235], v[186:189]
	v_mfma_f32_16x16x32_bf16 v[36:39], v[228:231], v[240:243], v[36:39]
	s_setprio 0
	s_barrier
	s_andn2_b64 vcc, exec, s[18:19]
	s_cbranch_vccnz .LBB0_892
	s_barrier
